# gMLP spatial phase: per-group global loads (W_s, v, u rows) issued together at the top of the group iteration instead of one-at-a-time ladder; static prio on waves 0-3
# speedup vs baseline: 1.0458x; 1.0056x over previous
; __global__ void __launch_bounds__(512) mega(Params p) {
;     extern __shared__ __attribute__((aligned(16))) char lds[];
;     cg::grid_group grid = cg::this_grid();
;     const int tid = threadIdx.x, wid = tid >> 6, lane = tid & 63;
_Z4mega6Params:
	s_load_dwordx2 s[28:29], s[0:1], 0x138
	s_load_dwordx2 s[68:69], s[0:1], 0xb0
	s_add_u32 s52, s0, 0x138
	v_writelane_b32 v254, s0, 0
	v_and_b32_e32 v168, 0x3ff, v0
	s_addc_u32 s53, s1, 0
	v_readfirstlane_b32 s4, v0
	s_nop 3
	s_and_b32 s4, s4, 0x3ff
	s_lshr_b32 s4, s4, 6
	s_cmp_lt_u32 s4, 4
	s_cbranch_scc0 .Lprio_done
	s_setprio 1

; DI bf16_t bf1(float a) { return (bf16_t)(pk2(a, 0.f) & 0xffffu); }
; DI float bflo(unsigned w) { return __uint_as_float(w << 16); }
; DI float bfhi(unsigned w) { return __uint_as_float(w & 0xffff0000u); }
; DI void spatial_phase(const bf16_t* __restrict__ z, const bf16_t* __restrict__ wsb, const float* __restrict__ vgain, const float* __restrict__ bs,
;                       bf16_t* __restrict__ y, char* lds, int tid, int wid, int lane) {
;     ...
;         for (int g = g0; g < g0 + 4; ++g) {
; #pragma unroll
;             for (int i = 0; i < 4; ++i) {
;                 const int id = tid + NTH * i, row = id >> 4, ch = id & 15;
;                 const u32x4 w = *(const u32x4*)(wsb + (long)(g * 128 + row) * 128 + ch * 8);
;                 *(u32x4*)(la + (ch >> 3) * 16384 + swz(row, ch & 7)) = w;
;                 const int q = row, d0 = ch * 8;
;                 const u32x4 vv = *(const u32x4*)(z + (t0 + q) * 2048 + 1024 + g * 128 + d0);
;                 const float rsq = srstd[q];
;                 const f32x4 g0 = *(const f32x4*)(vgain + g * 128 + d0), g1 = *(const f32x4*)(vgain + g * 128 + d0 + 4);
;                 float vals[8];
;                 vals[0] = bflo(vv.x) * rsq * g0.x; vals[1] = bfhi(vv.x) * rsq * g0.y; vals[2] = bflo(vv.y) * rsq * g0.z; vals[3] = bfhi(vv.y) * rsq * g0.w;
;                 vals[4] = bflo(vv.z) * rsq * g1.x; vals[5] = bfhi(vv.z) * rsq * g1.y; vals[6] = bflo(vv.w) * rsq * g1.z; vals[7] = bfhi(vv.w) * rsq * g1.w;
;                 char* dstb = lb + (q >> 6) * 16384 + (q & 7) * 2;
;                 const int qc = (q & 63) >> 3;
; #pragma unroll
;                 for (int e = 0; e < 8; ++e) *(bf16_t*)(dstb + swz(d0 + e, qc)) = bf1(vals[e]);
;             }
.LBB0_462:
	v_lshl_add_u64 v[4:5], v[48:49], 0, s[4:5]
	v_lshl_add_u64 v[8:9], v[50:51], 0, v[146:147]
	global_load_dwordx4 v[0:3], v[4:5], off offset:16
	s_nop 0
	global_load_dwordx4 v[4:7], v[4:5], off
	v_lshl_add_u64 v[220:221], v[50:51], 0, v[146:147]
	global_load_dwordx4 v[188:191], v[220:221], off
	v_lshl_add_u64 v[220:221], v[32:33], 0, v[146:147]
	v_add_co_u32_e32 v220, vcc, s51, v220
	s_nop 1
	v_addc_co_u32_e32 v221, vcc, 0, v221, vcc
	global_load_dwordx4 v[192:195], v[220:221], off offset:2048
	global_load_dwordx4 v[148:151], v[220:221], off
	v_lshl_add_u64 v[220:221], v[58:59], 0, v[146:147]
	global_load_dwordx4 v[196:199], v[220:221], off
	v_lshl_add_u64 v[220:221], v[34:35], 0, v[146:147]
	v_add_co_u32_e32 v220, vcc, s51, v220
	s_nop 1
	v_addc_co_u32_e32 v221, vcc, 0, v221, vcc
	global_load_dwordx4 v[200:203], v[220:221], off offset:2048
	global_load_dwordx4 v[152:155], v[220:221], off
	v_lshl_add_u64 v[220:221], v[56:57], 0, v[146:147]
	global_load_dwordx4 v[204:207], v[220:221], off
	v_lshl_add_u64 v[220:221], v[36:37], 0, v[146:147]
	v_add_co_u32_e32 v220, vcc, s51, v220
	s_nop 1
	v_addc_co_u32_e32 v221, vcc, 0, v221, vcc
	global_load_dwordx4 v[208:211], v[220:221], off offset:2048
	global_load_dwordx4 v[156:159], v[220:221], off
	v_lshl_add_u64 v[220:221], v[54:55], 0, v[146:147]
	global_load_dwordx4 v[212:215], v[220:221], off
	v_lshl_add_u64 v[220:221], v[38:39], 0, v[146:147]
	v_add_co_u32_e32 v220, vcc, s51, v220
	s_nop 1
	v_addc_co_u32_e32 v221, vcc, 0, v221, vcc
	global_load_dwordx4 v[216:219], v[220:221], off offset:2048
	global_load_dwordx4 v[160:163], v[220:221], off
	v_add_u32_e32 v120, v69, v74
	v_add_u32_e32 v130, v69, v75
	v_add_u32_e32 v131, v69, v76
	v_add_u32_e32 v132, v69, v77
	v_lshl_add_u64 v[50:51], v[50:51], 0, s[24:25]
	s_waitcnt vmcnt(11) lgkmcnt(0)
	v_mov_b32_e32 v8, v188
	v_mov_b32_e32 v9, v189
	v_mov_b32_e32 v10, v190
	v_mov_b32_e32 v11, v191
	ds_write_b128 v78, v[8:11]
	v_lshl_add_u64 v[8:9], v[32:33], 0, v[146:147]
	v_add_co_u32_e32 v66, vcc, s51, v8
	ds_read_b32 v12, v70
	s_nop 0
	v_addc_co_u32_e32 v67, vcc, 0, v9, vcc
	v_lshl_add_u64 v[32:33], v[32:33], 0, s[74:75]
	s_waitcnt vmcnt(10) lgkmcnt(0)
	v_mov_b32_e32 v8, v192
	v_mov_b32_e32 v9, v193
	v_mov_b32_e32 v10, v194
	v_mov_b32_e32 v11, v195
	v_lshlrev_b32_e32 v13, 16, v8
	v_and_b32_e32 v8, 0xffff0000, v8
	v_mul_f32_e32 v8, v12, v8
	v_lshlrev_b32_e32 v14, 16, v9
	v_mul_f32_e32 v8, v5, v8
	v_mul_f32_e32 v14, v12, v14
	v_and_b32_e32 v9, 0xffff0000, v9
	v_mul_f32_e32 v14, v6, v14
	v_mul_f32_e32 v9, v12, v9
	v_lshlrev_b32_e32 v15, 16, v10
	v_cvt_pk_bf16_f32 v8, v8, s0
	v_mul_f32_e32 v9, v7, v9
	v_mul_f32_e32 v15, v12, v15
	v_and_b32_e32 v10, 0xffff0000, v10
	ds_write_b16 v79, v8 offset:32896
	v_cvt_pk_bf16_f32 v8, v14, s0
	v_mul_f32_e32 v15, v0, v15
	v_mul_f32_e32 v10, v12, v10
	v_lshlrev_b32_e32 v16, 16, v11
	ds_write_b16 v80, v8 offset:32768
	v_cvt_pk_bf16_f32 v8, v9, s0
	v_mul_f32_e32 v10, v1, v10
	v_mul_f32_e32 v16, v12, v16
	v_and_b32_e32 v11, 0xffff0000, v11
	ds_write_b16 v81, v8 offset:32768
	v_cvt_pk_bf16_f32 v8, v15, s0
	v_mul_f32_e32 v16, v2, v16
	v_mul_f32_e32 v11, v12, v11
	ds_write_b16 v82, v8 offset:32768
	v_cvt_pk_bf16_f32 v8, v10, s0
	v_mul_f32_e32 v11, v3, v11
	ds_write_b16 v83, v8 offset:32768
	v_cvt_pk_bf16_f32 v8, v16, s0
	ds_write_b16 v84, v8 offset:32768
	v_cvt_pk_bf16_f32 v8, v11, s0
	ds_write_b16 v85, v8 offset:32768
	v_lshl_add_u64 v[8:9], v[58:59], 0, v[146:147]
	v_mul_f32_e32 v13, v12, v13
	v_mul_f32_e32 v13, v4, v13
	v_cvt_pk_bf16_f32 v12, v13, s0
	ds_write_b16 v79, v12 offset:32768
	v_lshl_add_u64 v[58:59], v[58:59], 0, s[24:25]
	s_waitcnt vmcnt(8) lgkmcnt(0)
	v_mov_b32_e32 v8, v196
	v_mov_b32_e32 v9, v197
	v_mov_b32_e32 v10, v198
	v_mov_b32_e32 v11, v199
	ds_write_b128 v86, v[8:11]
	v_lshl_add_u64 v[8:9], v[34:35], 0, v[146:147]
	v_add_co_u32_e32 v60, vcc, s51, v8
	ds_read_b32 v12, v71
	s_nop 0
	v_addc_co_u32_e32 v61, vcc, 0, v9, vcc
	v_lshl_add_u64 v[34:35], v[34:35], 0, s[74:75]
	s_waitcnt vmcnt(7) lgkmcnt(0)
	v_mov_b32_e32 v8, v200
	v_mov_b32_e32 v9, v201
	v_mov_b32_e32 v10, v202
	v_mov_b32_e32 v11, v203
	v_lshlrev_b32_e32 v13, 16, v8
	v_and_b32_e32 v8, 0xffff0000, v8
	v_mul_f32_e32 v8, v12, v8
	v_lshlrev_b32_e32 v14, 16, v9
	v_mul_f32_e32 v8, v5, v8
	v_mul_f32_e32 v14, v12, v14
	v_and_b32_e32 v9, 0xffff0000, v9
	v_mul_f32_e32 v14, v6, v14
	v_mul_f32_e32 v9, v12, v9
	v_lshlrev_b32_e32 v15, 16, v10
	v_cvt_pk_bf16_f32 v8, v8, s0
	v_mul_f32_e32 v9, v7, v9
	v_mul_f32_e32 v15, v12, v15
	v_and_b32_e32 v10, 0xffff0000, v10
	ds_write_b16 v87, v8 offset:32896
	v_cvt_pk_bf16_f32 v8, v14, s0
	v_mul_f32_e32 v15, v0, v15
	v_mul_f32_e32 v10, v12, v10
	v_lshlrev_b32_e32 v16, 16, v11
	ds_write_b16 v88, v8 offset:32768
	v_cvt_pk_bf16_f32 v8, v9, s0
	v_mul_f32_e32 v10, v1, v10
	v_mul_f32_e32 v16, v12, v16
	v_and_b32_e32 v11, 0xffff0000, v11
	ds_write_b16 v89, v8 offset:32768
	v_cvt_pk_bf16_f32 v8, v15, s0
	v_mul_f32_e32 v16, v2, v16
	v_mul_f32_e32 v11, v12, v11
	ds_write_b16 v90, v8 offset:32768
	v_cvt_pk_bf16_f32 v8, v10, s0
	v_mul_f32_e32 v11, v3, v11
	ds_write_b16 v91, v8 offset:32768
	v_cvt_pk_bf16_f32 v8, v16, s0
	ds_write_b16 v92, v8 offset:32768
	v_cvt_pk_bf16_f32 v8, v11, s0
	ds_write_b16 v93, v8 offset:32768
	v_lshl_add_u64 v[8:9], v[56:57], 0, v[146:147]
	v_mul_f32_e32 v13, v12, v13
	v_mul_f32_e32 v13, v4, v13
	v_cvt_pk_bf16_f32 v12, v13, s0
	ds_write_b16 v87, v12 offset:32768
	v_lshl_add_u64 v[56:57], v[56:57], 0, s[24:25]
	s_waitcnt vmcnt(5) lgkmcnt(0)
; #define MFMA(a, b, c) __builtin_amdgcn_mfma_f32_32x32x16_bf16((a), (b), (c), 0, 0, 0)
; DI bf16_t bf1(float a) { return (bf16_t)(pk2(a, 0.f) & 0xffffu); }
; DI float bflo(unsigned w) { return __uint_as_float(w << 16); }
; DI float bfhi(unsigned w) { return __uint_as_float(w & 0xffff0000u); }
; DI void spatial_phase(const bf16_t* __restrict__ z, const bf16_t* __restrict__ wsb, const float* __restrict__ vgain, const float* __restrict__ bs,
;                       bf16_t* __restrict__ y, char* lds, int tid, int wid, int lane) {
;     ...
;             for (int i = 0; i < 4; ++i) {
;                 const int id = tid + NTH * i, row = id >> 4, ch = id & 15;
;                 const u32x4 w = *(const u32x4*)(wsb + (long)(g * 128 + row) * 128 + ch * 8);
;                 *(u32x4*)(la + (ch >> 3) * 16384 + swz(row, ch & 7)) = w;
;                 const int q = row, d0 = ch * 8;
;                 const u32x4 vv = *(const u32x4*)(z + (t0 + q) * 2048 + 1024 + g * 128 + d0);
;                 const float rsq = srstd[q];
;                 const f32x4 g0 = *(const f32x4*)(vgain + g * 128 + d0), g1 = *(const f32x4*)(vgain + g * 128 + d0 + 4);
;                 float vals[8];
;                 vals[0] = bflo(vv.x) * rsq * g0.x; vals[1] = bfhi(vv.x) * rsq * g0.y; vals[2] = bflo(vv.y) * rsq * g0.z; vals[3] = bfhi(vv.y) * rsq * g0.w;
;                 vals[4] = bflo(vv.z) * rsq * g1.x; vals[5] = bfhi(vv.z) * rsq * g1.y; vals[6] = bflo(vv.w) * rsq * g1.z; vals[7] = bfhi(vv.w) * rsq * g1.w;
;                 char* dstb = lb + (q >> 6) * 16384 + (q & 7) * 2;
;                 const int qc = (q & 63) >> 3;
; #pragma unroll
;                 for (int e = 0; e < 8; ++e) *(bf16_t*)(dstb + swz(d0 + e, qc)) = bf1(vals[e]);
;             }
;             __syncthreads();
;             f32x16 acc[2];
; #pragma unroll
;             for (int n = 0; n < 2; ++n)
; #pragma unroll
;                 for (int i = 0; i < 16; ++i) acc[n][i] = 0.f;
; #pragma unroll
;             for (int kh = 0; kh < 2; ++kh)
; #pragma unroll
;                 for (int s = 0; s < 4; ++s) {
;                     const bf16x8 af = ldfrag(la + kh * 16384, wr * 32 + l31, 2 * s + hh);
; #pragma unroll
;                     for (int n = 0; n < 2; ++n) { const bf16x8 bfr = ldfrag(lb + kh * 16384, wc * 64 + n * 32 + l31, 2 * s + hh); acc[n] = MFMA(af, bfr, acc[n]); }
;                 }
	v_mov_b32_e32 v8, v204
	v_mov_b32_e32 v9, v205
	v_mov_b32_e32 v10, v206
	v_mov_b32_e32 v11, v207
	ds_write_b128 v94, v[8:11]
	v_lshl_add_u64 v[8:9], v[36:37], 0, v[146:147]
	v_add_co_u32_e32 v62, vcc, s51, v8
	ds_read_b32 v12, v72
	s_nop 0
	v_addc_co_u32_e32 v63, vcc, 0, v9, vcc
	v_lshl_add_u64 v[36:37], v[36:37], 0, s[74:75]
	s_waitcnt vmcnt(4) lgkmcnt(0)
	v_mov_b32_e32 v8, v208
	v_mov_b32_e32 v9, v209
	v_mov_b32_e32 v10, v210
	v_mov_b32_e32 v11, v211
	v_lshlrev_b32_e32 v13, 16, v8
	v_and_b32_e32 v8, 0xffff0000, v8
	v_mul_f32_e32 v8, v12, v8
	v_lshlrev_b32_e32 v14, 16, v9
	v_mul_f32_e32 v8, v5, v8
	v_mul_f32_e32 v14, v12, v14
	v_and_b32_e32 v9, 0xffff0000, v9
	v_mul_f32_e32 v14, v6, v14
	v_mul_f32_e32 v9, v12, v9
	v_lshlrev_b32_e32 v15, 16, v10
	v_cvt_pk_bf16_f32 v8, v8, s0
	v_mul_f32_e32 v9, v7, v9
	v_mul_f32_e32 v15, v12, v15
	v_and_b32_e32 v10, 0xffff0000, v10
	ds_write_b16 v95, v8 offset:32896
	v_cvt_pk_bf16_f32 v8, v14, s0
	v_mul_f32_e32 v15, v0, v15
	v_mul_f32_e32 v10, v12, v10
	v_lshlrev_b32_e32 v16, 16, v11
	ds_write_b16 v96, v8 offset:32768
	v_cvt_pk_bf16_f32 v8, v9, s0
	v_mul_f32_e32 v10, v1, v10
	v_mul_f32_e32 v16, v12, v16
	v_and_b32_e32 v11, 0xffff0000, v11
	ds_write_b16 v97, v8 offset:32768
	v_cvt_pk_bf16_f32 v8, v15, s0
	v_mul_f32_e32 v16, v2, v16
	v_mul_f32_e32 v11, v12, v11
	ds_write_b16 v98, v8 offset:32768
	v_cvt_pk_bf16_f32 v8, v10, s0
	v_mul_f32_e32 v11, v3, v11
	ds_write_b16 v99, v8 offset:32768
	v_cvt_pk_bf16_f32 v8, v16, s0
	ds_write_b16 v100, v8 offset:32768
	v_cvt_pk_bf16_f32 v8, v11, s0
	ds_write_b16 v101, v8 offset:32768
	v_lshl_add_u64 v[8:9], v[54:55], 0, v[146:147]
	v_mul_f32_e32 v13, v12, v13
	v_mul_f32_e32 v13, v4, v13
	v_cvt_pk_bf16_f32 v12, v13, s0
	ds_write_b16 v95, v12 offset:32768
	v_lshl_add_u64 v[54:55], v[54:55], 0, s[24:25]
	s_waitcnt vmcnt(2) lgkmcnt(0)
	v_mov_b32_e32 v8, v212
	v_mov_b32_e32 v9, v213
	v_mov_b32_e32 v10, v214
	v_mov_b32_e32 v11, v215
	ds_write_b128 v102, v[8:11]
	v_lshl_add_u64 v[8:9], v[38:39], 0, v[146:147]
	v_add_co_u32_e32 v64, vcc, s51, v8
	ds_read_b32 v12, v73
	s_nop 0
	v_addc_co_u32_e32 v65, vcc, 0, v9, vcc
	v_lshl_add_u64 v[38:39], v[38:39], 0, s[74:75]
	s_waitcnt vmcnt(1) lgkmcnt(0)
	v_mov_b32_e32 v8, v216
	v_mov_b32_e32 v9, v217
	v_mov_b32_e32 v10, v218
	v_mov_b32_e32 v11, v219
	v_lshlrev_b32_e32 v13, 16, v8
	v_and_b32_e32 v8, 0xffff0000, v8
	v_mul_f32_e32 v8, v12, v8
	v_mul_f32_e32 v5, v5, v8
	v_lshlrev_b32_e32 v8, 16, v9
	v_mul_f32_e32 v8, v12, v8
	v_mul_f32_e32 v6, v6, v8
	v_and_b32_e32 v8, 0xffff0000, v9
	v_mul_f32_e32 v8, v12, v8
	v_mul_f32_e32 v7, v7, v8
	v_lshlrev_b32_e32 v8, 16, v10
	v_mul_f32_e32 v8, v12, v8
	v_mul_f32_e32 v0, v0, v8
	v_and_b32_e32 v8, 0xffff0000, v10
	v_mul_f32_e32 v8, v12, v8
	v_mul_f32_e32 v13, v12, v13
	v_mul_f32_e32 v1, v1, v8
	v_lshlrev_b32_e32 v8, 16, v11
	v_mul_f32_e32 v4, v4, v13
	v_mul_f32_e32 v8, v12, v8
	v_mul_f32_e32 v2, v2, v8
	v_and_b32_e32 v8, 0xffff0000, v11
	v_cvt_pk_bf16_f32 v4, v4, s0
	v_cvt_pk_bf16_f32 v0, v0, s0
	v_mul_f32_e32 v8, v12, v8
	ds_write_b16 v103, v4 offset:32768
	v_cvt_pk_bf16_f32 v4, v5, s0
	ds_write_b16 v106, v0 offset:32768
	v_cvt_pk_bf16_f32 v0, v1, s0
	v_mul_f32_e32 v3, v3, v8
	ds_write_b16 v103, v4 offset:32896
	v_cvt_pk_bf16_f32 v4, v6, s0
	ds_write_b16 v107, v0 offset:32768
	v_cvt_pk_bf16_f32 v0, v2, s0
	ds_write_b16 v104, v4 offset:32768
	v_cvt_pk_bf16_f32 v4, v7, s0
	ds_write_b16 v108, v0 offset:32768
	v_cvt_pk_bf16_f32 v0, v3, s0
	ds_write_b16 v105, v4 offset:32768
	ds_write_b16 v109, v0 offset:32768
	s_waitcnt lgkmcnt(0)
	s_barrier
	ds_read_b128 v[0:3], v120
	ds_read_b128 v[4:7], v110 offset:32768
	s_waitcnt lgkmcnt(0)
	v_mfma_f32_32x32x16_bf16 v[16:31], v[0:3], v[4:7], 0
	ds_read_b128 v[4:7], v110 offset:36864
	ds_read_b128 v[122:125], v130
	ds_read_b128 v[126:129], v111 offset:32768
	s_waitcnt lgkmcnt(2)
	v_mfma_f32_32x32x16_bf16 v[0:15], v[0:3], v[4:7], 0
	s_waitcnt lgkmcnt(0)
	v_mfma_f32_32x32x16_bf16 v[16:31], v[122:125], v[126:129], v[16:31]
	ds_read_b128 v[126:129], v111 offset:36864
	s_waitcnt lgkmcnt(0)
	v_mfma_f32_32x32x16_bf16 v[0:15], v[122:125], v[126:129], v[0:15]
	ds_read_b128 v[122:125], v131
	ds_read_b128 v[126:129], v112 offset:32768
	s_waitcnt lgkmcnt(0)
	v_mfma_f32_32x32x16_bf16 v[16:31], v[122:125], v[126:129], v[16:31]
	ds_read_b128 v[126:129], v112 offset:36864
	s_waitcnt lgkmcnt(0)
	v_mfma_f32_32x32x16_bf16 v[0:15], v[122:125], v[126:129], v[0:15]
	ds_read_b128 v[122:125], v132
	ds_read_b128 v[126:129], v113 offset:32768
	s_waitcnt lgkmcnt(0)
	v_mfma_f32_32x32x16_bf16 v[16:31], v[122:125], v[126:129], v[16:31]
	ds_read_b128 v[126:129], v113 offset:36864
	s_waitcnt lgkmcnt(0)
	v_mfma_f32_32x32x16_bf16 v[0:15], v[122:125], v[126:129], v[0:15]
	ds_read_b128 v[120:123], v120 offset:16384
	ds_read_b128 v[124:127], v110 offset:49152
	s_waitcnt lgkmcnt(0)
	v_mfma_f32_32x32x16_bf16 v[16:31], v[120:123], v[124:127], v[16:31]
	ds_read_b128 v[124:127], v110 offset:53248
	s_waitcnt lgkmcnt(0)
	v_mfma_f32_32x32x16_bf16 v[0:15], v[120:123], v[124:127], v[0:15]
	ds_read_b128 v[120:123], v130 offset:16384
	ds_read_b128 v[124:127], v111 offset:49152
	s_waitcnt lgkmcnt(0)
	v_mfma_f32_32x32x16_bf16 v[16:31], v[120:123], v[124:127], v[16:31]
	ds_read_b128 v[124:127], v111 offset:53248
	s_waitcnt lgkmcnt(0)
	v_mfma_f32_32x32x16_bf16 v[0:15], v[120:123], v[124:127], v[0:15]
	ds_read_b128 v[120:123], v131 offset:16384
	ds_read_b128 v[124:127], v112 offset:49152
	s_waitcnt lgkmcnt(0)
	v_mfma_f32_32x32x16_bf16 v[16:31], v[120:123], v[124:127], v[16:31]
	ds_read_b128 v[124:127], v112 offset:53248
	s_waitcnt lgkmcnt(0)
; #define MFMA(a, b, c) __builtin_amdgcn_mfma_f32_32x32x16_bf16((a), (b), (c), 0, 0, 0)
; DI bf16_t bf1(float a) { return (bf16_t)(pk2(a, 0.f) & 0xffffu); }
; DI int crow(int i, int h) { return (i & 3) + 8 * (i >> 2) + 4 * h; }
; DI bf16x8 ldfrag(const char* lds, int row, int chunk) { return *(const bf16x8*)(lds + swz(row, chunk)); }
; DI void spatial_phase(const bf16_t* __restrict__ z, const bf16_t* __restrict__ wsb, const float* __restrict__ vgain, const float* __restrict__ bs,
;                       bf16_t* __restrict__ y, char* lds, int tid, int wid, int lane) {
;     ...
;             for (int kh = 0; kh < 2; ++kh)
; #pragma unroll
;                 for (int s = 0; s < 4; ++s) {
;                     const bf16x8 af = ldfrag(la + kh * 16384, wr * 32 + l31, 2 * s + hh);
; #pragma unroll
;                     for (int n = 0; n < 2; ++n) { const bf16x8 bfr = ldfrag(lb + kh * 16384, wc * 64 + n * 32 + l31, 2 * s + hh); acc[n] = MFMA(af, bfr, acc[n]); }
;                 }
;             char* vt_ = lds + 66048;
; #pragma unroll
;             for (int n = 0; n < 2; ++n)
; #pragma unroll
;                 for (int i = 0; i < 16; ++i) {
;                     const int p = wr * 32 + crow(i, hh), d = wc * 64 + n * 32 + l31;
;                     *(bf16_t*)(vt_ + p * 272 + d * 2) = bf1(acc[n][i] + bs[g * 128 + p]);
;                 }
;             __syncthreads();
	v_mfma_f32_32x32x16_bf16 v[0:15], v[120:123], v[124:127], v[0:15]
	ds_read_b128 v[120:123], v132 offset:16384
	ds_read_b128 v[124:127], v113 offset:49152
	s_waitcnt lgkmcnt(0)
	v_mfma_f32_32x32x16_bf16 v[16:31], v[120:123], v[124:127], v[16:31]
	ds_read_b128 v[124:127], v113 offset:53248
	s_waitcnt lgkmcnt(0)
	v_mfma_f32_32x32x16_bf16 v[0:15], v[120:123], v[124:127], v[0:15]
	v_lshl_add_u64 v[124:125], v[52:53], 0, s[4:5]
	global_load_dwordx4 v[120:123], v[124:125], off
	s_add_u32 s4, s4, 0x200
	s_addc_u32 s5, s5, 0
	s_cmpk_lg_i32 s4, 0x800
	s_waitcnt vmcnt(0)
	s_nop 2
	v_add_f32_e32 v16, v16, v120
	v_cvt_pk_bf16_f32 v16, v16, s0
	ds_write_b16 v114, v16
	v_add_f32_e32 v16, v17, v121
	v_cvt_pk_bf16_f32 v16, v16, s0
	ds_write_b16 v114, v16 offset:272
	v_add_f32_e32 v16, v18, v122
	v_cvt_pk_bf16_f32 v16, v16, s0
	ds_write_b16 v114, v16 offset:544
	v_add_f32_e32 v16, v19, v123
	v_cvt_pk_bf16_f32 v16, v16, s0
	ds_write_b16 v114, v16 offset:816
	global_load_dwordx4 v[16:19], v[124:125], off offset:32
	v_add_f32_e32 v0, v0, v120
	v_cvt_pk_bf16_f32 v0, v0, s0
	ds_write_b16 v115, v0
	v_add_f32_e32 v0, v1, v121
	v_cvt_pk_bf16_f32 v0, v0, s0
	ds_write_b16 v115, v0 offset:272
	v_add_f32_e32 v0, v2, v122
	v_cvt_pk_bf16_f32 v0, v0, s0
	ds_write_b16 v115, v0 offset:544
	v_add_f32_e32 v0, v3, v123
	v_cvt_pk_bf16_f32 v0, v0, s0
	ds_write_b16 v115, v0 offset:816
	s_waitcnt vmcnt(0)
	v_add_f32_e32 v20, v20, v16
	v_cvt_pk_bf16_f32 v20, v20, s0
	ds_write_b16 v114, v20 offset:2176
	v_add_f32_e32 v20, v21, v17
	v_cvt_pk_bf16_f32 v20, v20, s0
	ds_write_b16 v114, v20 offset:2448
	v_add_f32_e32 v20, v22, v18
	v_cvt_pk_bf16_f32 v20, v20, s0
	ds_write_b16 v114, v20 offset:2720
	v_add_f32_e32 v20, v23, v19
	v_cvt_pk_bf16_f32 v20, v20, s0
	ds_write_b16 v114, v20 offset:2992
	global_load_dwordx4 v[20:23], v[124:125], off offset:64
	v_add_f32_e32 v0, v4, v16
	v_cvt_pk_bf16_f32 v0, v0, s0
	ds_write_b16 v115, v0 offset:2176
	v_add_f32_e32 v0, v5, v17
	v_cvt_pk_bf16_f32 v0, v0, s0
	ds_write_b16 v115, v0 offset:2448
	v_add_f32_e32 v0, v6, v18
	v_cvt_pk_bf16_f32 v0, v0, s0
	ds_write_b16 v115, v0 offset:2720
	v_add_f32_e32 v0, v7, v19
	v_cvt_pk_bf16_f32 v0, v0, s0
	ds_write_b16 v115, v0 offset:2992
	s_waitcnt vmcnt(0)
	v_add_f32_e32 v24, v24, v20
	v_cvt_pk_bf16_f32 v24, v24, s0
	ds_write_b16 v114, v24 offset:4352
	v_add_f32_e32 v24, v25, v21
	v_cvt_pk_bf16_f32 v24, v24, s0
	ds_write_b16 v114, v24 offset:4624
	v_add_f32_e32 v24, v26, v22
	v_cvt_pk_bf16_f32 v24, v24, s0
	ds_write_b16 v114, v24 offset:4896
	v_add_f32_e32 v24, v27, v23
	v_cvt_pk_bf16_f32 v24, v24, s0
	ds_write_b16 v114, v24 offset:5168
	global_load_dwordx4 v[24:27], v[124:125], off offset:96
	v_add_f32_e32 v0, v8, v20
	v_cvt_pk_bf16_f32 v0, v0, s0
	ds_write_b16 v115, v0 offset:4352
	v_add_f32_e32 v0, v9, v21
	v_cvt_pk_bf16_f32 v0, v0, s0
	ds_write_b16 v115, v0 offset:4624
	v_add_f32_e32 v0, v10, v22
	v_cvt_pk_bf16_f32 v0, v0, s0
	ds_write_b16 v115, v0 offset:4896
	v_add_f32_e32 v0, v11, v23
	v_cvt_pk_bf16_f32 v0, v0, s0
	ds_write_b16 v115, v0 offset:5168
	s_waitcnt vmcnt(0)
	v_add_f32_e32 v28, v28, v24
	v_add_f32_e32 v0, v12, v24
	v_cvt_pk_bf16_f32 v28, v28, s0
	v_cvt_pk_bf16_f32 v0, v0, s0
	ds_write_b16 v114, v28 offset:6528
	v_add_f32_e32 v28, v29, v25
	ds_write_b16 v115, v0 offset:6528
	v_add_f32_e32 v0, v13, v25
	v_cvt_pk_bf16_f32 v28, v28, s0
	v_cvt_pk_bf16_f32 v0, v0, s0
	ds_write_b16 v114, v28 offset:6800
	v_add_f32_e32 v28, v30, v26
	ds_write_b16 v115, v0 offset:6800
	v_add_f32_e32 v0, v14, v26
	v_cvt_pk_bf16_f32 v28, v28, s0
	v_cvt_pk_bf16_f32 v0, v0, s0
	ds_write_b16 v114, v28 offset:7072
	v_add_f32_e32 v28, v31, v27
	ds_write_b16 v115, v0 offset:7072
	v_add_f32_e32 v0, v15, v27
	v_cvt_pk_bf16_f32 v28, v28, s0
	v_cvt_pk_bf16_f32 v0, v0, s0
	ds_write_b16 v114, v28 offset:7344
	ds_write_b16 v115, v0 offset:7344
	s_waitcnt lgkmcnt(0)
	s_barrier
; DI unsigned pk2(float a, float b) { f32x2 v = {a, b}; bf16x2_t r = __builtin_convertvector(v, bf16x2_t); return __builtin_bit_cast(unsigned, r); }
; DI float bflo(unsigned w) { return __uint_as_float(w << 16); }
; DI float bfhi(unsigned w) { return __uint_as_float(w & 0xffff0000u); }
; DI void spatial_phase(const bf16_t* __restrict__ z, const bf16_t* __restrict__ wsb, const float* __restrict__ vgain, const float* __restrict__ bs,
;                       bf16_t* __restrict__ y, char* lds, int tid, int wid, int lane) {
;     ...
;             for (int k = 0; k < 4; ++k) {
;                 const int id = tid + NTH * k, p = id >> 4, ch = id & 15;
;                 const u32x4 uu = *(const u32x4*)(z + (t0 + p) * 2048 + g * 128 + ch * 8);
;                 const u32x4 vv = *(const u32x4*)(vt_ + p * 272 + ch * 16);
;                 u32x4 o;
; #pragma unroll
;                 for (int e = 0; e < 4; ++e) o[e] = pk2(bflo(uu[e]) * bflo(vv[e]), bfhi(uu[e]) * bfhi(vv[e]));
;                 *(u32x4*)(y + (t0 + p) * 1024 + g * 128 + ch * 8) = o;
;             }
;             __syncthreads();
;         }
	ds_read_b128 v[4:7], v116
	s_waitcnt lgkmcnt(0)
	v_lshlrev_b32_e32 v10, 16, v4
	v_and_b32_e32 v11, 0xffff0000, v4
	v_lshlrev_b32_e32 v4, 16, v5
	v_and_b32_e32 v5, 0xffff0000, v5
	v_mov_b32_e32 v0, v148
	v_mov_b32_e32 v1, v149
	v_mov_b32_e32 v2, v150
	v_mov_b32_e32 v3, v151
	v_lshlrev_b32_e32 v8, 16, v0
	v_and_b32_e32 v9, 0xffff0000, v0
	v_pk_mul_f32 v[8:9], v[8:9], v[10:11]
	s_nop 0
	v_cvt_pk_bf16_f32 v0, v8, v9
	v_lshlrev_b32_e32 v8, 16, v1
	v_and_b32_e32 v9, 0xffff0000, v1
	v_pk_mul_f32 v[4:5], v[8:9], v[4:5]
	v_lshlrev_b32_e32 v8, 16, v6
	v_cvt_pk_bf16_f32 v1, v4, v5
	v_lshlrev_b32_e32 v4, 16, v2
	v_and_b32_e32 v5, 0xffff0000, v2
	v_and_b32_e32 v9, 0xffff0000, v6
	v_pk_mul_f32 v[4:5], v[4:5], v[8:9]
	v_lshlrev_b32_e32 v6, 16, v7
	v_cvt_pk_bf16_f32 v2, v4, v5
	v_lshlrev_b32_e32 v4, 16, v3
	v_and_b32_e32 v5, 0xffff0000, v3
	v_and_b32_e32 v7, 0xffff0000, v7
	v_pk_mul_f32 v[4:5], v[4:5], v[6:7]
	s_nop 0
	v_cvt_pk_bf16_f32 v3, v4, v5
	v_lshl_add_u64 v[4:5], v[40:41], 0, v[146:147]
	flat_store_dwordx4 v[4:5], v[0:3]
	ds_read_b128 v[4:7], v117
	v_lshl_add_u64 v[40:41], v[40:41], 0, s[74:75]
	s_waitcnt lgkmcnt(0)
	v_lshlrev_b32_e32 v10, 16, v4
	v_and_b32_e32 v11, 0xffff0000, v4
	v_lshlrev_b32_e32 v4, 16, v5
	v_and_b32_e32 v5, 0xffff0000, v5
	v_mov_b32_e32 v0, v152
	v_mov_b32_e32 v1, v153
	v_mov_b32_e32 v2, v154
	v_mov_b32_e32 v3, v155
	v_lshlrev_b32_e32 v8, 16, v0
	v_and_b32_e32 v9, 0xffff0000, v0
	v_pk_mul_f32 v[8:9], v[8:9], v[10:11]
	s_nop 0
	v_cvt_pk_bf16_f32 v0, v8, v9
	v_lshlrev_b32_e32 v8, 16, v1
	v_and_b32_e32 v9, 0xffff0000, v1
	v_pk_mul_f32 v[4:5], v[8:9], v[4:5]
	v_lshlrev_b32_e32 v8, 16, v6
	v_cvt_pk_bf16_f32 v1, v4, v5
	v_lshlrev_b32_e32 v4, 16, v2
	v_and_b32_e32 v5, 0xffff0000, v2
	v_and_b32_e32 v9, 0xffff0000, v6
	v_pk_mul_f32 v[4:5], v[4:5], v[8:9]
	v_lshlrev_b32_e32 v6, 16, v7
	v_cvt_pk_bf16_f32 v2, v4, v5
	v_lshlrev_b32_e32 v4, 16, v3
	v_and_b32_e32 v5, 0xffff0000, v3
	v_and_b32_e32 v7, 0xffff0000, v7
	v_pk_mul_f32 v[4:5], v[4:5], v[6:7]
	s_nop 0
	v_cvt_pk_bf16_f32 v3, v4, v5
	v_lshl_add_u64 v[4:5], v[42:43], 0, v[146:147]
	flat_store_dwordx4 v[4:5], v[0:3]
	ds_read_b128 v[4:7], v118
	v_lshl_add_u64 v[42:43], v[42:43], 0, s[74:75]
	s_waitcnt lgkmcnt(0)
	v_lshlrev_b32_e32 v10, 16, v4
	v_and_b32_e32 v11, 0xffff0000, v4
	v_lshlrev_b32_e32 v4, 16, v5
	v_and_b32_e32 v5, 0xffff0000, v5
	v_mov_b32_e32 v0, v156
	v_mov_b32_e32 v1, v157
	v_mov_b32_e32 v2, v158
	v_mov_b32_e32 v3, v159
	v_lshlrev_b32_e32 v8, 16, v0
	v_and_b32_e32 v9, 0xffff0000, v0
	v_pk_mul_f32 v[8:9], v[8:9], v[10:11]
	s_nop 0
	v_cvt_pk_bf16_f32 v0, v8, v9
	v_lshlrev_b32_e32 v8, 16, v1
	v_and_b32_e32 v9, 0xffff0000, v1
	v_pk_mul_f32 v[4:5], v[8:9], v[4:5]
	v_lshlrev_b32_e32 v8, 16, v6
	v_cvt_pk_bf16_f32 v1, v4, v5
	v_lshlrev_b32_e32 v4, 16, v2
	v_and_b32_e32 v5, 0xffff0000, v2
	v_and_b32_e32 v9, 0xffff0000, v6
	v_pk_mul_f32 v[4:5], v[4:5], v[8:9]
	v_lshlrev_b32_e32 v6, 16, v7
	v_cvt_pk_bf16_f32 v2, v4, v5
	v_lshlrev_b32_e32 v4, 16, v3
	v_and_b32_e32 v5, 0xffff0000, v3
	v_and_b32_e32 v7, 0xffff0000, v7
	v_pk_mul_f32 v[4:5], v[4:5], v[6:7]
	s_nop 0
	v_cvt_pk_bf16_f32 v3, v4, v5
	v_lshl_add_u64 v[4:5], v[44:45], 0, v[146:147]
	flat_store_dwordx4 v[4:5], v[0:3]
	ds_read_b128 v[4:7], v119
	v_lshl_add_u64 v[44:45], v[44:45], 0, s[74:75]
	s_waitcnt lgkmcnt(0)
	v_lshlrev_b32_e32 v10, 16, v4
	v_and_b32_e32 v11, 0xffff0000, v4
	v_lshlrev_b32_e32 v4, 16, v5
	v_and_b32_e32 v5, 0xffff0000, v5
	v_mov_b32_e32 v0, v160
	v_mov_b32_e32 v1, v161
	v_mov_b32_e32 v2, v162
	v_mov_b32_e32 v3, v163
	v_lshlrev_b32_e32 v8, 16, v0
	v_and_b32_e32 v9, 0xffff0000, v0
	v_pk_mul_f32 v[8:9], v[8:9], v[10:11]
	s_nop 0
	v_cvt_pk_bf16_f32 v0, v8, v9
	v_lshlrev_b32_e32 v8, 16, v1
	v_and_b32_e32 v9, 0xffff0000, v1
	v_pk_mul_f32 v[4:5], v[8:9], v[4:5]
	v_lshlrev_b32_e32 v8, 16, v6
	v_cvt_pk_bf16_f32 v1, v4, v5
	v_lshlrev_b32_e32 v4, 16, v2
	v_and_b32_e32 v5, 0xffff0000, v2
	v_and_b32_e32 v9, 0xffff0000, v6
	v_pk_mul_f32 v[4:5], v[4:5], v[8:9]
	v_lshlrev_b32_e32 v6, 16, v7
	v_cvt_pk_bf16_f32 v2, v4, v5
	v_lshlrev_b32_e32 v4, 16, v3
	v_and_b32_e32 v5, 0xffff0000, v3
	v_and_b32_e32 v7, 0xffff0000, v7
	v_pk_mul_f32 v[4:5], v[4:5], v[6:7]
	s_nop 0
	v_cvt_pk_bf16_f32 v3, v4, v5
	v_lshl_add_u64 v[4:5], v[46:47], 0, v[146:147]
	v_lshl_add_u64 v[46:47], v[46:47], 0, s[74:75]
	flat_store_dwordx4 v[4:5], v[0:3]
	s_waitcnt lgkmcnt(0)
	s_barrier
	s_cbranch_scc1 .LBB0_462
	s_add_i32 s31, s31, s28
	s_add_i32 s30, s30, s41
	s_cmpk_lt_i32 s31, 0x500
	s_cbranch_scc1 .LBB0_429
